# M2 layer 0 queue order: first 192 M2 units, then groups of (1 M2 unit + 5 weight-convert units) so convert HBM traffic overlaps compute-bound units (pure index bijection); on top of exact convert wait
# baseline (speedup 1.0000x reference)
;     __device__ __forceinline__ unsigned* ctl() const { return (unsigned*)(pp->ws + WS_CTL); }
; __device__ __forceinline__ int next_unit(Ctx& c, int q) {
;     ...
;     __syncthreads();
;     if (c.tid == 0) *slot = (int)__hip_atomic_fetch_add(c.ctl() + CW_Q + 64 * q, 1u, __ATOMIC_RELAXED, __HIP_MEMORY_SCOPE_AGENT);
;     __syncthreads();
;     return __builtin_amdgcn_readfirstlane(*slot);
; __device__ __forceinline__ void phase_M2(Ctx& c, int l, int q, const XcdBarrier& bar) {
;     ...
;     for (;;) {
;         const int u = next_unit(c, q);
;         const int pskip = ((int)gridDim.x == 256) ? PRO_NMOD : 0;
;         if (u >= M2_TOTAL + (l == 0 ? PRO_N - pskip : 0)) break;
;         if (u < M2_TOTAL) m2_dispatch(c, l, u); else prologue_unit(c, 1, pskip + u - M2_TOTAL);
.LBB0_1361:
	s_or_b64 exec, exec, s[0:1]
	s_waitcnt lgkmcnt(0)
	s_barrier
	s_load_dword s0, s[12:13], 0x0
	ds_read_b32 v0, v176
	s_waitcnt lgkmcnt(0)
	s_cmpk_eq_i32 s0, 0x100
	s_cselect_b32 s8, 0x60, 0
	v_readfirstlane_b32 s87, v0
	s_cmpk_lt_u32 s87, 0xc0
	s_cbranch_scc1 .Lil_done
	s_cmpk_ge_u32 s87, 0x600
	s_cbranch_scc1 .Lil_done
	s_sub_u32 s58, s87, 0xc0
	s_mul_hi_u32 s0, s58, 0xaaaaaaab
	s_lshr_b32 s0, s0, 2
	s_mul_i32 s87, s0, 6
	s_sub_u32 s58, s58, s87
	s_cmp_eq_u32 s58, 0
	s_cbranch_scc1 .Lil_m2
	s_mul_i32 s87, s0, 5
	s_add_u32 s87, s87, s58
	s_addk_i32 s87, 0x19f
	s_branch .Lil_done
.Lil_m2:
	s_add_u32 s87, s0, 0xc0
